# selection: score reads batched 8 in flight instead of 64 serialized LDS round trips
# speedup vs baseline: 1.0021x; 1.0021x over previous
.LBB0_160:
	v_mov_b32_e32 v70, 0
	s_and_b64 vcc, exec, s[0:1]
	v_mov_b32_e32 v0, 0
	s_mov_b32 s2, 0x7fff0000
	s_waitcnt lgkmcnt(0)
	s_barrier
	s_waitcnt lgkmcnt(0)
	ds_read_b32 v207, v114
	ds_read_b32 v208, v114 offset:256
	ds_read_b32 v209, v114 offset:512
	ds_read_b32 v210, v114 offset:768
	ds_read_b32 v211, v114 offset:1024
	ds_read_b32 v212, v114 offset:1280
	ds_read_b32 v213, v114 offset:1536
	ds_read_b32 v214, v114 offset:1792
	s_cbranch_vccz .LBB0_162
	s_waitcnt lgkmcnt(7)
	v_cvt_f16_f32_sdwa v0, v207 dst_sel:WORD_1 dst_unused:UNUSED_PAD src0_sel:DWORD
	s_nop 0
	v_bitop3_b32 v1, v0, s2, v0 bitop3:0xc
	v_cmp_gt_i32_e32 vcc, 0, v0
	s_nop 1
	v_cndmask_b32_e64 v0, -|v0|, v1, vcc
.LBB0_162:
	s_cmp_lt_i32 s38, 1
	s_cselect_b64 s[6:7], -1, 0
	s_and_b64 vcc, exec, s[6:7]
	s_cbranch_vccnz .LBB0_164
	s_waitcnt lgkmcnt(6)
	v_cvt_f16_f32_sdwa v1, v208 dst_sel:WORD_1 dst_unused:UNUSED_PAD src0_sel:DWORD
	s_nop 0
	v_bitop3_b32 v2, v1, s2, v1 bitop3:0xc
	v_cmp_gt_i32_e32 vcc, 0, v1
	s_nop 1
	v_cndmask_b32_e64 v70, -|v1|, v2, vcc
.LBB0_164:
	s_cmp_lt_i32 s38, 2
	s_cselect_b64 s[78:79], -1, 0
	v_mov_b32_e32 v69, 0
	s_and_b64 vcc, exec, s[78:79]
	v_mov_b32_e32 v72, 0
	s_cbranch_vccnz .LBB0_166
	s_waitcnt lgkmcnt(5)
	v_cvt_f16_f32_sdwa v1, v209 dst_sel:WORD_1 dst_unused:UNUSED_PAD src0_sel:DWORD
	s_nop 0
	v_bitop3_b32 v2, v1, s2, v1 bitop3:0xc
	v_cmp_gt_i32_e32 vcc, 0, v1
	s_nop 1
	v_cndmask_b32_e64 v72, -|v1|, v2, vcc
.LBB0_166:
	s_cmp_lt_i32 s38, 3
	s_cselect_b64 s[4:5], -1, 0
	s_and_b64 vcc, exec, s[4:5]
	s_cbranch_vccnz .LBB0_168
	s_waitcnt lgkmcnt(4)
	v_cvt_f16_f32_sdwa v1, v210 dst_sel:WORD_1 dst_unused:UNUSED_PAD src0_sel:DWORD
	s_nop 0
	v_bitop3_b32 v2, v1, s2, v1 bitop3:0xc
	v_cmp_gt_i32_e32 vcc, 0, v1
	s_nop 1
	v_cndmask_b32_e64 v69, -|v1|, v2, vcc
.LBB0_168:
	s_cmp_gt_i32 s38, 3
	v_mov_b32_e32 v67, 0
	s_cselect_b64 s[36:37], -1, 0
	s_cmp_lt_i32 s38, 4
	v_mov_b32_e32 v71, 0
	s_cbranch_scc1 .LBB0_170
	s_waitcnt lgkmcnt(3)
	v_cvt_f16_f32_sdwa v1, v211 dst_sel:WORD_1 dst_unused:UNUSED_PAD src0_sel:DWORD
	s_nop 0
	v_bitop3_b32 v2, v1, s2, v1 bitop3:0xc
	v_cmp_gt_i32_e32 vcc, 0, v1
	s_nop 1
	v_cndmask_b32_e64 v71, -|v1|, v2, vcc
.LBB0_170:
	s_cmp_gt_i32 s38, 4
	s_cselect_b64 s[58:59], -1, 0
	s_cmp_lt_i32 s38, 5
	s_cbranch_scc1 .LBB0_172
	s_waitcnt lgkmcnt(2)
	v_cvt_f16_f32_sdwa v1, v212 dst_sel:WORD_1 dst_unused:UNUSED_PAD src0_sel:DWORD
	s_nop 0
	v_bitop3_b32 v2, v1, s2, v1 bitop3:0xc
	v_cmp_gt_i32_e32 vcc, 0, v1
	s_nop 1
	v_cndmask_b32_e64 v67, -|v1|, v2, vcc
.LBB0_172:
	s_cmp_gt_i32 s38, 5
	v_mov_b32_e32 v65, 0
	s_cselect_b64 s[56:57], -1, 0
	s_cmp_lt_i32 s38, 6
	v_mov_b32_e32 v68, 0
	s_cbranch_scc1 .LBB0_174
	s_waitcnt lgkmcnt(1)
	v_cvt_f16_f32_sdwa v1, v213 dst_sel:WORD_1 dst_unused:UNUSED_PAD src0_sel:DWORD
	s_nop 0
	v_bitop3_b32 v2, v1, s2, v1 bitop3:0xc
	v_cmp_gt_i32_e32 vcc, 0, v1
	s_nop 1
	v_cndmask_b32_e64 v68, -|v1|, v2, vcc
.LBB0_174:
	s_cmp_gt_i32 s38, 6
	s_cselect_b64 s[48:49], -1, 0
	s_cmp_lt_i32 s38, 7
	s_cbranch_scc1 .LBB0_176
	s_waitcnt lgkmcnt(0)
	v_cvt_f16_f32_sdwa v1, v214 dst_sel:WORD_1 dst_unused:UNUSED_PAD src0_sel:DWORD
	s_nop 0
	v_bitop3_b32 v2, v1, s2, v1 bitop3:0xc
	v_cmp_gt_i32_e32 vcc, 0, v1
	s_nop 1
	v_cndmask_b32_e64 v65, -|v1|, v2, vcc
.LBB0_176:
	s_waitcnt lgkmcnt(0)
	ds_read_b32 v207, v114 offset:2048
	ds_read_b32 v208, v114 offset:2304
	ds_read_b32 v209, v114 offset:2560
	ds_read_b32 v210, v114 offset:2816
	ds_read_b32 v211, v114 offset:3072
	ds_read_b32 v212, v114 offset:3328
	ds_read_b32 v213, v114 offset:3584
	ds_read_b32 v214, v114 offset:3840
	s_cmp_gt_i32 s38, 7
	v_mov_b32_e32 v63, 0
	s_cselect_b64 s[34:35], -1, 0
	s_cmp_lt_i32 s38, 8
	v_mov_b32_e32 v66, 0
	s_cbranch_scc1 .LBB0_178
	s_waitcnt lgkmcnt(7)
	v_cvt_f16_f32_sdwa v1, v207 dst_sel:WORD_1 dst_unused:UNUSED_PAD src0_sel:DWORD
	s_nop 0
	v_bitop3_b32 v2, v1, s2, v1 bitop3:0xc
	v_cmp_gt_i32_e32 vcc, 0, v1
	s_nop 1
	v_cndmask_b32_e64 v66, -|v1|, v2, vcc
.LBB0_178:
	s_cmp_gt_i32 s38, 8
	s_cselect_b64 s[52:53], -1, 0
	s_cmp_lt_i32 s38, 9
	s_cbranch_scc1 .LBB0_180
	s_waitcnt lgkmcnt(6)
	v_cvt_f16_f32_sdwa v1, v208 dst_sel:WORD_1 dst_unused:UNUSED_PAD src0_sel:DWORD
	s_nop 0
	v_bitop3_b32 v2, v1, s2, v1 bitop3:0xc
	v_cmp_gt_i32_e32 vcc, 0, v1
	s_nop 1
	v_cndmask_b32_e64 v63, -|v1|, v2, vcc
.LBB0_180:
	s_cmp_gt_i32 s38, 9
	v_mov_b32_e32 v61, 0
	s_cselect_b64 s[28:29], -1, 0
	s_cmp_lt_i32 s38, 10
	v_mov_b32_e32 v64, 0
	s_cbranch_scc1 .LBB0_182
	s_waitcnt lgkmcnt(5)
	v_cvt_f16_f32_sdwa v1, v209 dst_sel:WORD_1 dst_unused:UNUSED_PAD src0_sel:DWORD
	s_nop 0
	v_bitop3_b32 v2, v1, s2, v1 bitop3:0xc
	v_cmp_gt_i32_e32 vcc, 0, v1
	s_nop 1
	v_cndmask_b32_e64 v64, -|v1|, v2, vcc
.LBB0_182:
	s_cmp_gt_i32 s38, 10
	s_cselect_b64 s[0:1], -1, 0
	v_writelane_b32 v253, s0, 47
	s_cmp_lt_i32 s38, 11
	s_nop 0
	v_writelane_b32 v253, s1, 48
	s_cbranch_scc1 .LBB0_184
	s_waitcnt lgkmcnt(4)
	v_cvt_f16_f32_sdwa v1, v210 dst_sel:WORD_1 dst_unused:UNUSED_PAD src0_sel:DWORD
	s_nop 0
	v_bitop3_b32 v2, v1, s2, v1 bitop3:0xc
	v_cmp_gt_i32_e32 vcc, 0, v1
	s_nop 1
	v_cndmask_b32_e64 v61, -|v1|, v2, vcc
.LBB0_184:
	s_cmp_gt_i32 s38, 11
	s_cselect_b64 s[0:1], -1, 0
	v_writelane_b32 v253, s0, 49
	v_mov_b32_e32 v59, 0
	s_cmp_lt_i32 s38, 12
	v_writelane_b32 v253, s1, 50
	v_mov_b32_e32 v62, 0
	s_cbranch_scc1 .LBB0_186
	s_waitcnt lgkmcnt(3)
	v_cvt_f16_f32_sdwa v1, v211 dst_sel:WORD_1 dst_unused:UNUSED_PAD src0_sel:DWORD
	s_nop 0
	v_bitop3_b32 v2, v1, s2, v1 bitop3:0xc
	v_cmp_gt_i32_e32 vcc, 0, v1
	s_nop 1
	v_cndmask_b32_e64 v62, -|v1|, v2, vcc
.LBB0_186:
	s_cmp_gt_i32 s38, 12
	s_cselect_b64 s[0:1], -1, 0
	v_writelane_b32 v253, s0, 51
	s_cmp_lt_i32 s38, 13
	s_nop 0
	v_writelane_b32 v253, s1, 52
	s_cbranch_scc1 .LBB0_188
	s_waitcnt lgkmcnt(2)
	v_cvt_f16_f32_sdwa v1, v212 dst_sel:WORD_1 dst_unused:UNUSED_PAD src0_sel:DWORD
	s_nop 0
	v_bitop3_b32 v2, v1, s2, v1 bitop3:0xc
	v_cmp_gt_i32_e32 vcc, 0, v1
	s_nop 1
	v_cndmask_b32_e64 v59, -|v1|, v2, vcc
.LBB0_188:
	s_cmp_gt_i32 s38, 13
	s_cselect_b64 s[0:1], -1, 0
	v_writelane_b32 v253, s0, 53
	v_mov_b32_e32 v57, 0
	s_cmp_lt_i32 s38, 14
	v_writelane_b32 v253, s1, 54
	v_mov_b32_e32 v60, 0
	s_cbranch_scc1 .LBB0_190
	s_waitcnt lgkmcnt(1)
	v_cvt_f16_f32_sdwa v1, v213 dst_sel:WORD_1 dst_unused:UNUSED_PAD src0_sel:DWORD
	s_nop 0
	v_bitop3_b32 v2, v1, s2, v1 bitop3:0xc
	v_cmp_gt_i32_e32 vcc, 0, v1
	s_nop 1
	v_cndmask_b32_e64 v60, -|v1|, v2, vcc
.LBB0_190:
	s_cmp_gt_i32 s38, 14
	s_cselect_b64 s[0:1], -1, 0
	v_writelane_b32 v253, s0, 55
	s_cmp_lt_i32 s38, 15
	s_nop 0
	v_writelane_b32 v253, s1, 56
	s_cbranch_scc1 .LBB0_192
	s_waitcnt lgkmcnt(0)
	v_cvt_f16_f32_sdwa v1, v214 dst_sel:WORD_1 dst_unused:UNUSED_PAD src0_sel:DWORD
	s_nop 0
	v_bitop3_b32 v2, v1, s2, v1 bitop3:0xc
	v_cmp_gt_i32_e32 vcc, 0, v1
	s_nop 1
	v_cndmask_b32_e64 v57, -|v1|, v2, vcc
.LBB0_192:
	s_waitcnt lgkmcnt(0)
	ds_read_b32 v207, v114 offset:4096
	ds_read_b32 v208, v114 offset:4352
	ds_read_b32 v209, v114 offset:4608
	ds_read_b32 v210, v114 offset:4864
	ds_read_b32 v211, v114 offset:5120
	ds_read_b32 v212, v114 offset:5376
	ds_read_b32 v213, v114 offset:5632
	ds_read_b32 v214, v114 offset:5888
	s_cmp_gt_i32 s38, 15
	v_mov_b32_e32 v55, 0
	s_cselect_b64 s[50:51], -1, 0
	s_cmp_lt_i32 s38, 16
	v_mov_b32_e32 v58, 0
	s_cbranch_scc1 .LBB0_194
	s_waitcnt lgkmcnt(7)
	v_cvt_f16_f32_sdwa v1, v207 dst_sel:WORD_1 dst_unused:UNUSED_PAD src0_sel:DWORD
	s_nop 0
	v_bitop3_b32 v2, v1, s2, v1 bitop3:0xc
	v_cmp_gt_i32_e32 vcc, 0, v1
	s_nop 1
	v_cndmask_b32_e64 v58, -|v1|, v2, vcc
.LBB0_194:
	s_cmp_gt_i32 s38, 16
	s_cselect_b64 s[0:1], -1, 0
	v_writelane_b32 v253, s0, 57
	s_cmp_lt_i32 s38, 17
	s_nop 0
	v_writelane_b32 v253, s1, 58
	s_cbranch_scc1 .LBB0_196
	s_waitcnt lgkmcnt(6)
	v_cvt_f16_f32_sdwa v1, v208 dst_sel:WORD_1 dst_unused:UNUSED_PAD src0_sel:DWORD
	s_nop 0
	v_bitop3_b32 v2, v1, s2, v1 bitop3:0xc
	v_cmp_gt_i32_e32 vcc, 0, v1
	s_nop 1
	v_cndmask_b32_e64 v55, -|v1|, v2, vcc
.LBB0_196:
	s_cmp_gt_i32 s38, 17
	s_cselect_b64 s[0:1], -1, 0
	v_writelane_b32 v253, s0, 59
	v_mov_b32_e32 v53, 0
	s_cmp_lt_i32 s38, 18
	v_writelane_b32 v253, s1, 60
	v_mov_b32_e32 v56, 0
	s_cbranch_scc1 .LBB0_198
	s_waitcnt lgkmcnt(5)
	v_cvt_f16_f32_sdwa v1, v209 dst_sel:WORD_1 dst_unused:UNUSED_PAD src0_sel:DWORD
	s_nop 0
	v_bitop3_b32 v2, v1, s2, v1 bitop3:0xc
	v_cmp_gt_i32_e32 vcc, 0, v1
	s_nop 1
	v_cndmask_b32_e64 v56, -|v1|, v2, vcc
.LBB0_198:
	s_cmp_gt_i32 s38, 18
	s_cselect_b64 s[0:1], -1, 0
	v_writelane_b32 v253, s0, 61
	s_cmp_lt_i32 s38, 19
	s_nop 0
	v_writelane_b32 v253, s1, 62
	s_cbranch_scc1 .LBB0_200
	s_waitcnt lgkmcnt(4)
	v_cvt_f16_f32_sdwa v1, v210 dst_sel:WORD_1 dst_unused:UNUSED_PAD src0_sel:DWORD
	s_nop 0
	v_bitop3_b32 v2, v1, s2, v1 bitop3:0xc
	v_cmp_gt_i32_e32 vcc, 0, v1
	s_nop 1
	v_cndmask_b32_e64 v53, -|v1|, v2, vcc
.LBB0_200:
	s_cmp_gt_i32 s38, 19
	s_cselect_b64 s[0:1], -1, 0
	v_mov_b32_e32 v51, 0
	v_writelane_b32 v253, s0, 63
	s_cmp_lt_i32 s38, 20
	v_mov_b32_e32 v54, 0
	v_writelane_b32 v254, s1, 0
	s_cbranch_scc1 .LBB0_202
	s_waitcnt lgkmcnt(3)
	v_cvt_f16_f32_sdwa v1, v211 dst_sel:WORD_1 dst_unused:UNUSED_PAD src0_sel:DWORD
	s_nop 0
	v_bitop3_b32 v2, v1, s2, v1 bitop3:0xc
	v_cmp_gt_i32_e32 vcc, 0, v1
	s_nop 1
	v_cndmask_b32_e64 v54, -|v1|, v2, vcc
.LBB0_202:
	s_cmp_gt_i32 s38, 20
	s_cselect_b64 s[0:1], -1, 0
	v_writelane_b32 v254, s0, 1
	s_cmp_lt_i32 s38, 21
	s_nop 0
	v_writelane_b32 v254, s1, 2
	s_cbranch_scc1 .LBB0_204
	s_waitcnt lgkmcnt(2)
	v_cvt_f16_f32_sdwa v1, v212 dst_sel:WORD_1 dst_unused:UNUSED_PAD src0_sel:DWORD
	s_nop 0
	v_bitop3_b32 v2, v1, s2, v1 bitop3:0xc
	v_cmp_gt_i32_e32 vcc, 0, v1
	s_nop 1
	v_cndmask_b32_e64 v51, -|v1|, v2, vcc
.LBB0_204:
	s_cmp_gt_i32 s38, 21
	s_cselect_b64 s[0:1], -1, 0
	v_writelane_b32 v254, s0, 3
	v_mov_b32_e32 v49, 0
	s_cmp_lt_i32 s38, 22
	v_writelane_b32 v254, s1, 4
	v_mov_b32_e32 v52, 0
	s_cbranch_scc1 .LBB0_206
	s_waitcnt lgkmcnt(1)
	v_cvt_f16_f32_sdwa v1, v213 dst_sel:WORD_1 dst_unused:UNUSED_PAD src0_sel:DWORD
	s_nop 0
	v_bitop3_b32 v2, v1, s2, v1 bitop3:0xc
	v_cmp_gt_i32_e32 vcc, 0, v1
	s_nop 1
	v_cndmask_b32_e64 v52, -|v1|, v2, vcc
.LBB0_206:
	s_cmp_gt_i32 s38, 22
	s_cselect_b64 s[0:1], -1, 0
	v_writelane_b32 v254, s0, 5
	s_cmp_lt_i32 s38, 23
	s_nop 0
	v_writelane_b32 v254, s1, 6
	s_cbranch_scc1 .LBB0_208
	s_waitcnt lgkmcnt(0)
	v_cvt_f16_f32_sdwa v1, v214 dst_sel:WORD_1 dst_unused:UNUSED_PAD src0_sel:DWORD
	s_nop 0
	v_bitop3_b32 v2, v1, s2, v1 bitop3:0xc
	v_cmp_gt_i32_e32 vcc, 0, v1
	s_nop 1
	v_cndmask_b32_e64 v49, -|v1|, v2, vcc
.LBB0_208:
	s_waitcnt lgkmcnt(0)
	ds_read_b32 v207, v114 offset:6144
	ds_read_b32 v208, v114 offset:6400
	ds_read_b32 v209, v114 offset:6656
	ds_read_b32 v210, v114 offset:6912
	ds_read_b32 v211, v114 offset:7168
	ds_read_b32 v212, v114 offset:7424
	ds_read_b32 v213, v114 offset:7680
	ds_read_b32 v214, v114 offset:7936
	s_cmp_gt_i32 s38, 23
	v_mov_b32_e32 v47, 0
	s_cselect_b64 s[68:69], -1, 0
	s_cmp_lt_i32 s38, 24
	v_mov_b32_e32 v50, 0
	s_cbranch_scc1 .LBB0_210
	s_waitcnt lgkmcnt(7)
	v_cvt_f16_f32_sdwa v1, v207 dst_sel:WORD_1 dst_unused:UNUSED_PAD src0_sel:DWORD
	s_nop 0
	v_bitop3_b32 v2, v1, s2, v1 bitop3:0xc
	v_cmp_gt_i32_e32 vcc, 0, v1
	s_nop 1
	v_cndmask_b32_e64 v50, -|v1|, v2, vcc
.LBB0_210:
	s_cmp_gt_i32 s38, 24
	s_cselect_b64 s[0:1], -1, 0
	v_writelane_b32 v254, s0, 7
	s_cmp_lt_i32 s38, 25
	s_nop 0
	v_writelane_b32 v254, s1, 8
	s_cbranch_scc1 .LBB0_212
	s_waitcnt lgkmcnt(6)
	v_cvt_f16_f32_sdwa v1, v208 dst_sel:WORD_1 dst_unused:UNUSED_PAD src0_sel:DWORD
	s_nop 0
	v_bitop3_b32 v2, v1, s2, v1 bitop3:0xc
	v_cmp_gt_i32_e32 vcc, 0, v1
	s_nop 1
	v_cndmask_b32_e64 v47, -|v1|, v2, vcc
.LBB0_212:
	s_cmp_gt_i32 s38, 25
	s_cselect_b64 s[0:1], -1, 0
	v_writelane_b32 v254, s0, 9
	v_mov_b32_e32 v45, 0
	s_cmp_lt_i32 s38, 26
	v_writelane_b32 v254, s1, 10
	v_mov_b32_e32 v48, 0
	s_cbranch_scc1 .LBB0_214
	s_waitcnt lgkmcnt(5)
	v_cvt_f16_f32_sdwa v1, v209 dst_sel:WORD_1 dst_unused:UNUSED_PAD src0_sel:DWORD
	s_nop 0
	v_bitop3_b32 v2, v1, s2, v1 bitop3:0xc
	v_cmp_gt_i32_e32 vcc, 0, v1
	s_nop 1
	v_cndmask_b32_e64 v48, -|v1|, v2, vcc
.LBB0_214:
	s_cmp_gt_i32 s38, 26
	s_cselect_b64 s[0:1], -1, 0
	v_writelane_b32 v254, s0, 11
	s_cmp_lt_i32 s38, 27
	s_nop 0
	v_writelane_b32 v254, s1, 12
	s_cbranch_scc1 .LBB0_216
	s_waitcnt lgkmcnt(4)
	v_cvt_f16_f32_sdwa v1, v210 dst_sel:WORD_1 dst_unused:UNUSED_PAD src0_sel:DWORD
	s_nop 0
	v_bitop3_b32 v2, v1, s2, v1 bitop3:0xc
	v_cmp_gt_i32_e32 vcc, 0, v1
	s_nop 1
	v_cndmask_b32_e64 v45, -|v1|, v2, vcc
.LBB0_216:
	s_cmp_gt_i32 s38, 27
	s_cselect_b64 s[0:1], -1, 0
	v_writelane_b32 v254, s0, 13
	v_mov_b32_e32 v43, 0
	s_cmp_lt_i32 s38, 28
	v_writelane_b32 v254, s1, 14
	v_mov_b32_e32 v46, 0
	s_cbranch_scc1 .LBB0_218
	s_waitcnt lgkmcnt(3)
	v_cvt_f16_f32_sdwa v1, v211 dst_sel:WORD_1 dst_unused:UNUSED_PAD src0_sel:DWORD
	s_nop 0
	v_bitop3_b32 v2, v1, s2, v1 bitop3:0xc
	v_cmp_gt_i32_e32 vcc, 0, v1
	s_nop 1
	v_cndmask_b32_e64 v46, -|v1|, v2, vcc
.LBB0_218:
	s_cmp_gt_i32 s38, 28
	s_cselect_b64 s[0:1], -1, 0
	v_writelane_b32 v254, s0, 15
	s_cmp_lt_i32 s38, 29
	s_nop 0
	v_writelane_b32 v254, s1, 16
	s_cbranch_scc1 .LBB0_220
	s_waitcnt lgkmcnt(2)
	v_cvt_f16_f32_sdwa v1, v212 dst_sel:WORD_1 dst_unused:UNUSED_PAD src0_sel:DWORD
	s_nop 0
	v_bitop3_b32 v2, v1, s2, v1 bitop3:0xc
	v_cmp_gt_i32_e32 vcc, 0, v1
	s_nop 1
	v_cndmask_b32_e64 v43, -|v1|, v2, vcc
.LBB0_220:
	s_cmp_gt_i32 s38, 29
	s_cselect_b64 s[0:1], -1, 0
	v_writelane_b32 v254, s0, 17
	v_mov_b32_e32 v41, 0
	s_cmp_lt_i32 s38, 30
	v_writelane_b32 v254, s1, 18
	v_mov_b32_e32 v44, 0
	s_cbranch_scc1 .LBB0_222
	s_waitcnt lgkmcnt(1)
	v_cvt_f16_f32_sdwa v1, v213 dst_sel:WORD_1 dst_unused:UNUSED_PAD src0_sel:DWORD
	s_nop 0
	v_bitop3_b32 v2, v1, s2, v1 bitop3:0xc
	v_cmp_gt_i32_e32 vcc, 0, v1
	s_nop 1
	v_cndmask_b32_e64 v44, -|v1|, v2, vcc
.LBB0_222:
	s_cmp_gt_i32 s38, 30
	s_cselect_b64 s[0:1], -1, 0
	v_writelane_b32 v254, s0, 19
	s_cmp_lt_i32 s38, 31
	s_nop 0
	v_writelane_b32 v254, s1, 20
	s_cbranch_scc1 .LBB0_224
	s_waitcnt lgkmcnt(0)
	v_cvt_f16_f32_sdwa v1, v214 dst_sel:WORD_1 dst_unused:UNUSED_PAD src0_sel:DWORD
	s_nop 0
	v_bitop3_b32 v2, v1, s2, v1 bitop3:0xc
	v_cmp_gt_i32_e32 vcc, 0, v1
	s_nop 1
	v_cndmask_b32_e64 v41, -|v1|, v2, vcc
.LBB0_224:
	s_waitcnt lgkmcnt(0)
	ds_read_b32 v207, v114 offset:8192
	ds_read_b32 v208, v114 offset:8448
	ds_read_b32 v209, v114 offset:8704
	ds_read_b32 v210, v114 offset:8960
	ds_read_b32 v211, v114 offset:9216
	ds_read_b32 v212, v114 offset:9472
	ds_read_b32 v213, v114 offset:9728
	ds_read_b32 v214, v114 offset:9984
	s_cmp_gt_i32 s38, 31
	v_mov_b32_e32 v31, 0
	s_cselect_b64 s[0:1], -1, 0
	s_cmp_lt_i32 s38, 32
	v_mov_b32_e32 v42, 0
	s_cbranch_scc1 .LBB0_226
	s_waitcnt lgkmcnt(7)
	v_cvt_f16_f32_sdwa v1, v207 dst_sel:WORD_1 dst_unused:UNUSED_PAD src0_sel:DWORD
	s_nop 0
	v_bitop3_b32 v2, v1, s2, v1 bitop3:0xc
	v_cmp_gt_i32_e32 vcc, 0, v1
	s_nop 1
	v_cndmask_b32_e64 v42, -|v1|, v2, vcc
.LBB0_226:
	s_cmp_gt_i32 s38, 32
	s_cselect_b64 s[24:25], -1, 0
	v_writelane_b32 v254, s24, 21
	s_cmp_lt_i32 s38, 33
	s_nop 0
	v_writelane_b32 v254, s25, 22
	s_cbranch_scc1 .LBB0_228
	s_waitcnt lgkmcnt(6)
	v_cvt_f16_f32_sdwa v1, v208 dst_sel:WORD_1 dst_unused:UNUSED_PAD src0_sel:DWORD
	s_nop 0
	v_bitop3_b32 v2, v1, s2, v1 bitop3:0xc
	v_cmp_gt_i32_e32 vcc, 0, v1
	s_nop 1
	v_cndmask_b32_e64 v31, -|v1|, v2, vcc
.LBB0_228:
	s_cmp_gt_i32 s38, 33
	s_cselect_b64 s[24:25], -1, 0
	v_writelane_b32 v254, s24, 23
	v_mov_b32_e32 v29, 0
	s_cmp_lt_i32 s38, 34
	v_writelane_b32 v254, s25, 24
	v_mov_b32_e32 v40, 0
	s_cbranch_scc1 .LBB0_230
	s_waitcnt lgkmcnt(5)
	v_cvt_f16_f32_sdwa v1, v209 dst_sel:WORD_1 dst_unused:UNUSED_PAD src0_sel:DWORD
	s_nop 0
	v_bitop3_b32 v2, v1, s2, v1 bitop3:0xc
	v_cmp_gt_i32_e32 vcc, 0, v1
	s_nop 1
	v_cndmask_b32_e64 v40, -|v1|, v2, vcc
.LBB0_230:
	s_cmp_gt_i32 s38, 34
	s_cselect_b64 s[24:25], -1, 0
	v_writelane_b32 v254, s24, 25
	s_cmp_lt_i32 s38, 35
	s_nop 0
	v_writelane_b32 v254, s25, 26
	s_cbranch_scc1 .LBB0_232
	s_waitcnt lgkmcnt(4)
	v_cvt_f16_f32_sdwa v1, v210 dst_sel:WORD_1 dst_unused:UNUSED_PAD src0_sel:DWORD
	s_nop 0
	v_bitop3_b32 v2, v1, s2, v1 bitop3:0xc
	v_cmp_gt_i32_e32 vcc, 0, v1
	s_nop 1
	v_cndmask_b32_e64 v29, -|v1|, v2, vcc
.LBB0_232:
	s_cmp_gt_i32 s38, 35
	s_cselect_b64 s[24:25], -1, 0
	v_writelane_b32 v254, s24, 27
	v_mov_b32_e32 v27, 0
	s_cmp_lt_i32 s38, 36
	v_writelane_b32 v254, s25, 28
	v_mov_b32_e32 v30, 0
	s_cbranch_scc1 .LBB0_234
	s_waitcnt lgkmcnt(3)
	v_cvt_f16_f32_sdwa v1, v211 dst_sel:WORD_1 dst_unused:UNUSED_PAD src0_sel:DWORD
	s_nop 0
	v_bitop3_b32 v2, v1, s2, v1 bitop3:0xc
	v_cmp_gt_i32_e32 vcc, 0, v1
	s_nop 1
	v_cndmask_b32_e64 v30, -|v1|, v2, vcc
.LBB0_234:
	s_cmp_gt_i32 s38, 36
	s_cselect_b64 s[24:25], -1, 0
	v_writelane_b32 v254, s24, 29
	s_cmp_lt_i32 s38, 37
	s_nop 0
	v_writelane_b32 v254, s25, 30
	s_cbranch_scc1 .LBB0_236
	s_waitcnt lgkmcnt(2)
	v_cvt_f16_f32_sdwa v1, v212 dst_sel:WORD_1 dst_unused:UNUSED_PAD src0_sel:DWORD
	s_nop 0
	v_bitop3_b32 v2, v1, s2, v1 bitop3:0xc
	v_cmp_gt_i32_e32 vcc, 0, v1
	s_nop 1
	v_cndmask_b32_e64 v27, -|v1|, v2, vcc
.LBB0_236:
	s_cmp_gt_i32 s38, 37
	s_cselect_b64 s[24:25], -1, 0
	v_writelane_b32 v254, s24, 31
	v_mov_b32_e32 v25, 0
	s_cmp_lt_i32 s38, 38
	v_writelane_b32 v254, s25, 32
	v_mov_b32_e32 v28, 0
	s_cbranch_scc1 .LBB0_238
	s_waitcnt lgkmcnt(1)
	v_cvt_f16_f32_sdwa v1, v213 dst_sel:WORD_1 dst_unused:UNUSED_PAD src0_sel:DWORD
	s_nop 0
	v_bitop3_b32 v2, v1, s2, v1 bitop3:0xc
	v_cmp_gt_i32_e32 vcc, 0, v1
	s_nop 1
	v_cndmask_b32_e64 v28, -|v1|, v2, vcc
.LBB0_238:
	s_cmp_gt_i32 s38, 38
	s_cselect_b64 s[24:25], -1, 0
	v_writelane_b32 v254, s24, 33
	s_cmp_lt_i32 s38, 39
	s_nop 0
	v_writelane_b32 v254, s25, 34
	s_cbranch_scc1 .LBB0_240
	s_waitcnt lgkmcnt(0)
	v_cvt_f16_f32_sdwa v1, v214 dst_sel:WORD_1 dst_unused:UNUSED_PAD src0_sel:DWORD
	s_nop 0
	v_bitop3_b32 v2, v1, s2, v1 bitop3:0xc
	v_cmp_gt_i32_e32 vcc, 0, v1
	s_nop 1
	v_cndmask_b32_e64 v25, -|v1|, v2, vcc
.LBB0_240:
	s_waitcnt lgkmcnt(0)
	ds_read_b32 v207, v114 offset:10240
	ds_read_b32 v208, v114 offset:10496
	ds_read_b32 v209, v114 offset:10752
	ds_read_b32 v210, v114 offset:11008
	ds_read_b32 v211, v114 offset:11264
	ds_read_b32 v212, v114 offset:11520
	ds_read_b32 v213, v114 offset:11776
	ds_read_b32 v214, v114 offset:12032
	s_cmp_gt_i32 s38, 39
	v_mov_b32_e32 v23, 0
	s_cselect_b64 s[30:31], -1, 0
	s_cmp_lt_i32 s38, 40
	v_mov_b32_e32 v26, 0
	s_cbranch_scc1 .LBB0_242
	s_waitcnt lgkmcnt(7)
	v_cvt_f16_f32_sdwa v1, v207 dst_sel:WORD_1 dst_unused:UNUSED_PAD src0_sel:DWORD
	s_nop 0
	v_bitop3_b32 v2, v1, s2, v1 bitop3:0xc
	v_cmp_gt_i32_e32 vcc, 0, v1
	s_nop 1
	v_cndmask_b32_e64 v26, -|v1|, v2, vcc
.LBB0_242:
	s_cmp_gt_i32 s38, 40
	s_cselect_b64 s[24:25], -1, 0
	v_writelane_b32 v254, s24, 35
	s_cmp_lt_i32 s38, 41
	s_nop 0
	v_writelane_b32 v254, s25, 36
	s_cbranch_scc1 .LBB0_244
	s_waitcnt lgkmcnt(6)
	v_cvt_f16_f32_sdwa v1, v208 dst_sel:WORD_1 dst_unused:UNUSED_PAD src0_sel:DWORD
	s_nop 0
	v_bitop3_b32 v2, v1, s2, v1 bitop3:0xc
	v_cmp_gt_i32_e32 vcc, 0, v1
	s_nop 1
	v_cndmask_b32_e64 v23, -|v1|, v2, vcc
.LBB0_244:
	s_cmp_gt_i32 s38, 41
	s_cselect_b64 s[24:25], -1, 0
	v_writelane_b32 v254, s24, 37
	v_mov_b32_e32 v21, 0
	s_cmp_lt_i32 s38, 42
	v_writelane_b32 v254, s25, 38
	v_mov_b32_e32 v24, 0
	s_cbranch_scc1 .LBB0_246
	s_waitcnt lgkmcnt(5)
	v_cvt_f16_f32_sdwa v1, v209 dst_sel:WORD_1 dst_unused:UNUSED_PAD src0_sel:DWORD
	s_nop 0
	v_bitop3_b32 v2, v1, s2, v1 bitop3:0xc
	v_cmp_gt_i32_e32 vcc, 0, v1
	s_nop 1
	v_cndmask_b32_e64 v24, -|v1|, v2, vcc
.LBB0_246:
	s_cmp_gt_i32 s38, 42
	s_cselect_b64 s[24:25], -1, 0
	v_writelane_b32 v254, s24, 39
	s_cmp_lt_i32 s38, 43
	s_nop 0
	v_writelane_b32 v254, s25, 40
	s_cbranch_scc1 .LBB0_248
	s_waitcnt lgkmcnt(4)
	v_cvt_f16_f32_sdwa v1, v210 dst_sel:WORD_1 dst_unused:UNUSED_PAD src0_sel:DWORD
	s_nop 0
	v_bitop3_b32 v2, v1, s2, v1 bitop3:0xc
	v_cmp_gt_i32_e32 vcc, 0, v1
	s_nop 1
	v_cndmask_b32_e64 v21, -|v1|, v2, vcc
.LBB0_248:
	s_cmp_gt_i32 s38, 43
	s_cselect_b64 s[24:25], -1, 0
	v_writelane_b32 v254, s24, 41
	v_mov_b32_e32 v19, 0
	s_cmp_lt_i32 s38, 44
	v_writelane_b32 v254, s25, 42
	v_mov_b32_e32 v22, 0
	s_cbranch_scc1 .LBB0_250
	s_waitcnt lgkmcnt(3)
	v_cvt_f16_f32_sdwa v1, v211 dst_sel:WORD_1 dst_unused:UNUSED_PAD src0_sel:DWORD
	s_nop 0
	v_bitop3_b32 v2, v1, s2, v1 bitop3:0xc
	v_cmp_gt_i32_e32 vcc, 0, v1
	s_nop 1
	v_cndmask_b32_e64 v22, -|v1|, v2, vcc
.LBB0_250:
	s_cmp_gt_i32 s38, 44
	s_cselect_b64 s[24:25], -1, 0
	v_writelane_b32 v254, s24, 43
	s_cmp_lt_i32 s38, 45
	s_nop 0
	v_writelane_b32 v254, s25, 44
	s_cbranch_scc1 .LBB0_252
	s_waitcnt lgkmcnt(2)
	v_cvt_f16_f32_sdwa v1, v212 dst_sel:WORD_1 dst_unused:UNUSED_PAD src0_sel:DWORD
	s_nop 0
	v_bitop3_b32 v2, v1, s2, v1 bitop3:0xc
	v_cmp_gt_i32_e32 vcc, 0, v1
	s_nop 1
	v_cndmask_b32_e64 v19, -|v1|, v2, vcc
.LBB0_252:
	s_cmp_gt_i32 s38, 45
	s_cselect_b64 s[24:25], -1, 0
	v_writelane_b32 v254, s24, 45
	v_mov_b32_e32 v17, 0
	s_cmp_lt_i32 s38, 46
	v_writelane_b32 v254, s25, 46
	v_mov_b32_e32 v20, 0
	s_cbranch_scc1 .LBB0_254
	s_waitcnt lgkmcnt(1)
	v_cvt_f16_f32_sdwa v1, v213 dst_sel:WORD_1 dst_unused:UNUSED_PAD src0_sel:DWORD
	s_nop 0
	v_bitop3_b32 v2, v1, s2, v1 bitop3:0xc
	v_cmp_gt_i32_e32 vcc, 0, v1
	s_nop 1
	v_cndmask_b32_e64 v20, -|v1|, v2, vcc
.LBB0_254:
	s_cmp_gt_i32 s38, 46
	s_cselect_b64 s[24:25], -1, 0
	v_writelane_b32 v254, s24, 47
	s_cmp_lt_i32 s38, 47
	s_nop 0
	v_writelane_b32 v254, s25, 48
	s_cbranch_scc1 .LBB0_256
	s_waitcnt lgkmcnt(0)
	v_cvt_f16_f32_sdwa v1, v214 dst_sel:WORD_1 dst_unused:UNUSED_PAD src0_sel:DWORD
	s_nop 0
	v_bitop3_b32 v2, v1, s2, v1 bitop3:0xc
	v_cmp_gt_i32_e32 vcc, 0, v1
	s_nop 1
	v_cndmask_b32_e64 v17, -|v1|, v2, vcc
.LBB0_256:
	s_waitcnt lgkmcnt(0)
	ds_read_b32 v207, v114 offset:12288
	ds_read_b32 v208, v114 offset:12544
	ds_read_b32 v209, v114 offset:12800
	ds_read_b32 v210, v114 offset:13056
	ds_read_b32 v211, v114 offset:13312
	ds_read_b32 v212, v114 offset:13568
	ds_read_b32 v213, v114 offset:13824
	ds_read_b32 v214, v114 offset:14080
	s_cmp_gt_i32 s38, 47
	v_mov_b32_e32 v15, 0
	s_cselect_b64 s[54:55], -1, 0
	s_cmp_lt_i32 s38, 48
	v_mov_b32_e32 v18, 0
	s_cbranch_scc1 .LBB0_258
	s_waitcnt lgkmcnt(7)
	v_cvt_f16_f32_sdwa v1, v207 dst_sel:WORD_1 dst_unused:UNUSED_PAD src0_sel:DWORD
	s_nop 0
	v_bitop3_b32 v2, v1, s2, v1 bitop3:0xc
	v_cmp_gt_i32_e32 vcc, 0, v1
	s_nop 1
	v_cndmask_b32_e64 v18, -|v1|, v2, vcc
.LBB0_258:
	s_cmp_gt_i32 s38, 48
	s_cselect_b64 s[24:25], -1, 0
	v_writelane_b32 v254, s24, 49
	s_cmp_lt_i32 s38, 49
	s_nop 0
	v_writelane_b32 v254, s25, 50
	s_cbranch_scc1 .LBB0_260
	s_waitcnt lgkmcnt(6)
	v_cvt_f16_f32_sdwa v1, v208 dst_sel:WORD_1 dst_unused:UNUSED_PAD src0_sel:DWORD
	s_nop 0
	v_bitop3_b32 v2, v1, s2, v1 bitop3:0xc
	v_cmp_gt_i32_e32 vcc, 0, v1
	s_nop 1
	v_cndmask_b32_e64 v15, -|v1|, v2, vcc
.LBB0_260:
	s_cmp_gt_i32 s38, 49
	s_cselect_b64 s[24:25], -1, 0
	v_writelane_b32 v254, s24, 51
	v_mov_b32_e32 v13, 0
	s_cmp_lt_i32 s38, 50
	v_writelane_b32 v254, s25, 52
	v_mov_b32_e32 v16, 0
	s_cbranch_scc1 .LBB0_262
	s_waitcnt lgkmcnt(5)
	v_cvt_f16_f32_sdwa v1, v209 dst_sel:WORD_1 dst_unused:UNUSED_PAD src0_sel:DWORD
	s_nop 0
	v_bitop3_b32 v2, v1, s2, v1 bitop3:0xc
	v_cmp_gt_i32_e32 vcc, 0, v1
	s_nop 1
	v_cndmask_b32_e64 v16, -|v1|, v2, vcc
.LBB0_262:
	s_cmp_gt_i32 s38, 50
	s_cselect_b64 s[24:25], -1, 0
	v_writelane_b32 v254, s24, 53
	s_cmp_lt_i32 s38, 51
	s_nop 0
	v_writelane_b32 v254, s25, 54
	s_cbranch_scc1 .LBB0_264
	s_waitcnt lgkmcnt(4)
	v_cvt_f16_f32_sdwa v1, v210 dst_sel:WORD_1 dst_unused:UNUSED_PAD src0_sel:DWORD
	s_nop 0
	v_bitop3_b32 v2, v1, s2, v1 bitop3:0xc
	v_cmp_gt_i32_e32 vcc, 0, v1
	s_nop 1
	v_cndmask_b32_e64 v13, -|v1|, v2, vcc
.LBB0_264:
	s_cmp_gt_i32 s38, 51
	s_cselect_b64 s[24:25], -1, 0
	v_writelane_b32 v254, s24, 55
	v_mov_b32_e32 v11, 0
	s_cmp_lt_i32 s38, 52
	v_writelane_b32 v254, s25, 56
	v_mov_b32_e32 v14, 0
	s_cbranch_scc1 .LBB0_266
	s_waitcnt lgkmcnt(3)
	v_cvt_f16_f32_sdwa v1, v211 dst_sel:WORD_1 dst_unused:UNUSED_PAD src0_sel:DWORD
	s_nop 0
	v_bitop3_b32 v2, v1, s2, v1 bitop3:0xc
	v_cmp_gt_i32_e32 vcc, 0, v1
	s_nop 1
	v_cndmask_b32_e64 v14, -|v1|, v2, vcc
.LBB0_266:
	s_cmp_gt_i32 s38, 52
	s_cselect_b64 s[24:25], -1, 0
	v_writelane_b32 v254, s24, 57
	s_cmp_lt_i32 s38, 53
	s_nop 0
	v_writelane_b32 v254, s25, 58
	s_cbranch_scc1 .LBB0_268
	s_waitcnt lgkmcnt(2)
	v_cvt_f16_f32_sdwa v1, v212 dst_sel:WORD_1 dst_unused:UNUSED_PAD src0_sel:DWORD
	s_nop 0
	v_bitop3_b32 v2, v1, s2, v1 bitop3:0xc
	v_cmp_gt_i32_e32 vcc, 0, v1
	s_nop 1
	v_cndmask_b32_e64 v11, -|v1|, v2, vcc
.LBB0_268:
	s_cmp_gt_i32 s38, 53
	s_cselect_b64 s[24:25], -1, 0
	v_writelane_b32 v254, s24, 59
	v_mov_b32_e32 v9, 0
	s_cmp_lt_i32 s38, 54
	v_writelane_b32 v254, s25, 60
	v_mov_b32_e32 v12, 0
	s_cbranch_scc1 .LBB0_270
	s_waitcnt lgkmcnt(1)
	v_cvt_f16_f32_sdwa v1, v213 dst_sel:WORD_1 dst_unused:UNUSED_PAD src0_sel:DWORD
	s_nop 0
	v_bitop3_b32 v2, v1, s2, v1 bitop3:0xc
	v_cmp_gt_i32_e32 vcc, 0, v1
	s_nop 1
	v_cndmask_b32_e64 v12, -|v1|, v2, vcc
.LBB0_270:
	s_cmp_gt_i32 s38, 54
	s_cselect_b64 s[24:25], -1, 0
	v_writelane_b32 v254, s24, 61
	s_cmp_lt_i32 s38, 55
	s_nop 0
	v_writelane_b32 v254, s25, 62
	s_cbranch_scc1 .LBB0_272
	s_waitcnt lgkmcnt(0)
	v_cvt_f16_f32_sdwa v1, v214 dst_sel:WORD_1 dst_unused:UNUSED_PAD src0_sel:DWORD
	s_nop 0
	v_bitop3_b32 v2, v1, s2, v1 bitop3:0xc
	v_cmp_gt_i32_e32 vcc, 0, v1
	s_nop 1
	v_cndmask_b32_e64 v9, -|v1|, v2, vcc
.LBB0_272:
	s_waitcnt lgkmcnt(0)
	ds_read_b32 v207, v114 offset:14336
	ds_read_b32 v208, v114 offset:14592
	ds_read_b32 v209, v114 offset:14848
	ds_read_b32 v210, v114 offset:15104
	ds_read_b32 v211, v114 offset:15360
	ds_read_b32 v212, v114 offset:15616
	ds_read_b32 v213, v114 offset:15872
	ds_read_b32 v214, v114 offset:16128
	s_cmp_gt_i32 s38, 55
	v_mov_b32_e32 v7, 0
	s_cselect_b64 s[24:25], -1, 0
	s_cmp_lt_i32 s38, 56
	v_mov_b32_e32 v10, 0
	s_cbranch_scc1 .LBB0_274
	s_waitcnt lgkmcnt(7)
	v_cvt_f16_f32_sdwa v1, v207 dst_sel:WORD_1 dst_unused:UNUSED_PAD src0_sel:DWORD
	s_nop 0
	v_bitop3_b32 v2, v1, s2, v1 bitop3:0xc
	v_cmp_gt_i32_e32 vcc, 0, v1
	s_nop 1
	v_cndmask_b32_e64 v10, -|v1|, v2, vcc
.LBB0_274:
	s_cmp_gt_i32 s38, 56
	s_cselect_b64 s[40:41], -1, 0
	v_writelane_b32 v253, s40, 33
	s_cmp_lt_i32 s38, 57
	s_nop 0
	v_writelane_b32 v253, s41, 34
	s_cbranch_scc1 .LBB0_276
	s_waitcnt lgkmcnt(6)
	v_cvt_f16_f32_sdwa v1, v208 dst_sel:WORD_1 dst_unused:UNUSED_PAD src0_sel:DWORD
	s_nop 0
	v_bitop3_b32 v2, v1, s2, v1 bitop3:0xc
	v_cmp_gt_i32_e32 vcc, 0, v1
	s_nop 1
	v_cndmask_b32_e64 v7, -|v1|, v2, vcc
.LBB0_276:
	s_cmp_gt_i32 s38, 57
	s_cselect_b64 s[40:41], -1, 0
	v_writelane_b32 v253, s40, 27
	v_mov_b32_e32 v5, 0
	s_cmp_lt_i32 s38, 58
	v_writelane_b32 v253, s41, 28
	v_mov_b32_e32 v8, 0
	s_cbranch_scc1 .LBB0_278
	s_waitcnt lgkmcnt(5)
	v_cvt_f16_f32_sdwa v1, v209 dst_sel:WORD_1 dst_unused:UNUSED_PAD src0_sel:DWORD
	s_nop 0
	v_bitop3_b32 v2, v1, s2, v1 bitop3:0xc
	v_cmp_gt_i32_e32 vcc, 0, v1
	s_nop 1
	v_cndmask_b32_e64 v8, -|v1|, v2, vcc
.LBB0_278:
	s_cmp_gt_i32 s38, 58
	s_cselect_b64 s[40:41], -1, 0
	v_writelane_b32 v253, s40, 25
	s_cmp_lt_i32 s38, 59
	s_nop 0
	v_writelane_b32 v253, s41, 26
	s_cbranch_scc1 .LBB0_280
	s_waitcnt lgkmcnt(4)
	v_cvt_f16_f32_sdwa v1, v210 dst_sel:WORD_1 dst_unused:UNUSED_PAD src0_sel:DWORD
	s_nop 0
	v_bitop3_b32 v2, v1, s2, v1 bitop3:0xc
	v_cmp_gt_i32_e32 vcc, 0, v1
	s_nop 1
	v_cndmask_b32_e64 v5, -|v1|, v2, vcc
.LBB0_280:
	s_cmp_gt_i32 s38, 59
	s_cselect_b64 s[40:41], -1, 0
	v_writelane_b32 v253, s40, 31
	v_mov_b32_e32 v3, 0
	s_cmp_lt_i32 s38, 60
	v_writelane_b32 v253, s41, 32
	v_mov_b32_e32 v6, 0
	s_cbranch_scc1 .LBB0_282
	s_waitcnt lgkmcnt(3)
	v_cvt_f16_f32_sdwa v1, v211 dst_sel:WORD_1 dst_unused:UNUSED_PAD src0_sel:DWORD
	s_nop 0
	v_bitop3_b32 v2, v1, s2, v1 bitop3:0xc
	v_cmp_gt_i32_e32 vcc, 0, v1
	s_nop 1
	v_cndmask_b32_e64 v6, -|v1|, v2, vcc
.LBB0_282:
	s_cmp_gt_i32 s38, 60
	s_cselect_b64 s[40:41], -1, 0
	v_writelane_b32 v253, s40, 29
	s_cmp_lt_i32 s38, 61
	s_nop 0
	v_writelane_b32 v253, s41, 30
	s_cbranch_scc1 .LBB0_284
	s_waitcnt lgkmcnt(2)
	v_cvt_f16_f32_sdwa v1, v212 dst_sel:WORD_1 dst_unused:UNUSED_PAD src0_sel:DWORD
	s_nop 0
	v_bitop3_b32 v2, v1, s2, v1 bitop3:0xc
	v_cmp_gt_i32_e32 vcc, 0, v1
	s_nop 1
	v_cndmask_b32_e64 v3, -|v1|, v2, vcc
.LBB0_284:
	s_cmp_gt_i32 s38, 61
	s_cselect_b64 s[40:41], -1, 0
	v_writelane_b32 v253, s40, 23
	v_mov_b32_e32 v2, 0
	s_cmp_lt_i32 s38, 62
	v_writelane_b32 v253, s41, 24
	v_mov_b32_e32 v4, 0
	s_cbranch_scc1 .LBB0_286
	s_waitcnt lgkmcnt(1)
	v_cvt_f16_f32_sdwa v1, v213 dst_sel:WORD_1 dst_unused:UNUSED_PAD src0_sel:DWORD
	s_nop 0
	v_bitop3_b32 v4, v1, s2, v1 bitop3:0xc
	v_cmp_gt_i32_e32 vcc, 0, v1
	s_nop 1
	v_cndmask_b32_e64 v4, -|v1|, v4, vcc
.LBB0_286:
	s_cmp_gt_i32 s38, 62
	s_cselect_b64 s[40:41], -1, 0
	v_writelane_b32 v253, s40, 21
	s_cmp_lt_i32 s38, 63
	s_nop 0
	v_writelane_b32 v253, s41, 22
	s_cbranch_scc1 .LBB0_288
	s_waitcnt lgkmcnt(0)
	v_cvt_f16_f32_sdwa v1, v214 dst_sel:WORD_1 dst_unused:UNUSED_PAD src0_sel:DWORD
	s_nop 0
	v_bitop3_b32 v2, v1, s2, v1 bitop3:0xc
	v_cmp_gt_i32_e32 vcc, 0, v1
	s_nop 1
	v_cndmask_b32_e64 v2, -|v1|, v2, vcc
.LBB0_288:
	s_waitcnt lgkmcnt(0)
	s_add_i32 s2, s27, s22
	s_ashr_i32 s3, s2, 31
	s_lshl_b64 s[2:3], s[2:3], 10
	s_add_u32 s2, s26, s2
	s_addc_u32 s3, s76, s3
	s_andn2_b64 vcc, exec, s[36:37]
	s_cbranch_vccnz .LBB0_306
	v_writelane_b32 v253, s4, 45
	s_mov_b32 s27, 31
	s_nop 0
	v_writelane_b32 v253, s5, 46
	s_mov_b32 s4, s26
	s_mov_b32 s5, s83
	s_mov_b32 s83, 0
